# code placement: all code after the GDN prep first-item branch shifted by 8 bytes
# baseline (speedup 1.0000x reference)
.LBB0_44:
	v_ashrrev_i32_e32 v2, 9, v46
	v_ashrrev_i32_e32 v3, 31, v2
	s_waitcnt lgkmcnt(0)
	s_barrier
	v_readlane_b32 s0, v254, 37
	v_and_b32_e32 v0, 63, v46
	v_bfe_u32 v7, v46, 6, 3
	v_lshlrev_b64 v[82:83], 12, v[2:3]
	v_readlane_b32 s1, v254, 38
	v_cmp_eq_u32_e32 vcc, s0, v46
	v_lshl_or_b32 v82, v0, 6, v82
	s_and_b64 s[0:1], s[6:7], vcc
	v_lshlrev_b32_e32 v84, 7, v7
	s_and_saveexec_b64 s[20:21], s[0:1]
	s_cbranch_execz .LBB0_63
	s_nop 0
	s_nop 0
	v_lshrrev_b32_e32 v3, 6, v46
	v_and_b32_e32 v3, 7, v3
	v_cmp_ne_u32_e32 vcc, 0, v0
	v_lshl_or_b32 v0, v2, 6, v0
	v_lshl_add_u32 v6, v3, 7, v154
	v_add_u32_e32 v9, 0x700, v84
	v_lshl_add_u32 v14, v0, 1, v0
	s_mov_b64 s[24:25], 0
	v_mov_b32_e32 v15, v155
	v_mov_b32_e32 v8, v166
	s_branch .LBB0_47
